# adds cross-attention Q*K^T blocks: four dependent 8-MFMA chains interleaved with 2-3 LDS reads in flight instead of one read + lgkmcnt(0) per MFMA
# baseline (speedup 1.0000x reference)
; DI int ltid() { int t = threadIdx.x; asm volatile("" : "+v"(t)); return t; }
; #define load_tile(kt) do { \
;     kreg0 = *reinterpret_cast<const uint4*>(kbase0 + (size_t)(kt) * 64 * 1024); \
;     kreg1 = *reinterpret_cast<const uint4*>(kbase1 + (size_t)(kt) * 64 * 1024); \
;     vreg0 = *reinterpret_cast<const uint4*>(vbase0 + (kt) * 64); \
;     vreg1 = *reinterpret_cast<const uint4*>(vbase1 + (kt) * 64); } while (0)
; #define store_tile() do { \
;     *reinterpret_cast<uint4*>(kdst0) = kreg0; *reinterpret_cast<uint4*>(kdst1) = kreg1; \
;     *reinterpret_cast<uint4*>(vdst0) = vreg0; *reinterpret_cast<uint4*>(vdst1) = vreg1; } while (0)
;   DI void tile(const u16* Ks, const u16* Vts) {
;     ...
;     const int lane = ltid() & 63, fr = lane & 15, fq = lane >> 4;
;     float base[NQB];
; #pragma unroll
;     for (int qb = 0; qb < NQB; ++qb) base[qb] = (m[qb] == -INFINITY) ? 0.f : m[qb];
;     f32x4 s[4][NQB];
;     __builtin_amdgcn_s_setprio(1);
; #pragma unroll
;     for (int kb = 0; kb < 4; ++kb) {
; #pragma unroll
;       for (int qb = 0; qb < NQB; ++qb) s[kb][qb] = f32x4{-base[qb], -base[qb], -base[qb], -base[qb]};
; #pragma unroll
;       for (int ks = 0; ks < DK / 32; ++ks) {
;         bf16x8 kf = *reinterpret_cast<const bf16x8*>(Ks + (kb * 16 + fr) * KSTR + ks * 32 + fq * 8);
; #pragma unroll
;         for (int qb = 0; qb < NQB; ++qb) s[kb][qb] = __builtin_amdgcn_mfma_f32_16x16x32_bf16(kf, qf[qb][ks], s[kb][qb], 0, 0, 0);
;       }
;     }
; DI void cross_attn_item(const PRef& p, int tokblk, int h) {
;     ...
;   load_tile(0);
;   for (int kt = 0; kt < 4; ++kt) {
;     __syncthreads();
;     store_tile();
;     __syncthreads();
;     if (kt + 1 < 4) load_tile(kt + 1);
;     fw.tile(Ks, Vts);
.LBB0_145:
	v_lshl_add_u64 v[0:1], s[2:3], 0, v[230:231]
	s_mov_b32 s14, 0x6120000
	v_add_co_u32_e32 v2, vcc, s14, v0
	s_mov_b32 s14, 0x6128000
	s_nop 0
	v_addc_co_u32_e32 v3, vcc, 0, v1, vcc
	v_add_co_u32_e32 v6, vcc, s14, v0
	s_mov_b32 s14, 0x6130000
	s_nop 0
	v_addc_co_u32_e32 v7, vcc, 0, v1, vcc
	s_barrier
	s_waitcnt vmcnt(5)
	ds_write_b128 v250, v[120:123]
	ds_write_b128 v250, v[116:119] offset:8448
	ds_write_b128 v250, v[124:127] offset:16896
	s_waitcnt vmcnt(3)
	ds_write_b128 v250, v[128:131] offset:25344
	ds_write_b128 v249, v[132:135] offset:33792
	s_waitcnt vmcnt(2)
	ds_write_b128 v249, v[136:139] offset:43008
	s_waitcnt vmcnt(1)
	ds_write_b128 v249, v[140:143] offset:52224
	s_waitcnt vmcnt(0)
	ds_write_b128 v249, v[144:147] offset:61440
	s_waitcnt lgkmcnt(0)
	s_barrier
	global_load_dwordx4 v[120:123], v[2:3], off
	global_load_dwordx4 v[116:119], v[6:7], off
	v_add_co_u32_e32 v2, vcc, s14, v0
	s_mov_b32 s14, 0x6138000
	s_nop 0
	v_addc_co_u32_e32 v3, vcc, 0, v1, vcc
	v_add_co_u32_e32 v0, vcc, s14, v0
	s_mov_b32 s14, 0x6500000
	s_nop 0
	v_addc_co_u32_e32 v1, vcc, 0, v1, vcc
	global_load_dwordx4 v[124:127], v[2:3], off
	global_load_dwordx4 v[128:131], v[0:1], off
	v_lshl_add_u64 v[0:1], s[2:3], 0, v[232:233]
	v_add_co_u32_e32 v2, vcc, s14, v0
	s_mov_b32 s14, 0x6540000
	s_nop 0
	v_addc_co_u32_e32 v3, vcc, 0, v1, vcc
	v_add_co_u32_e32 v6, vcc, s14, v0
	s_mov_b32 s14, 0x6580000
	s_nop 0
	v_addc_co_u32_e32 v7, vcc, 0, v1, vcc
	global_load_dwordx4 v[132:135], v[2:3], off offset:128
	global_load_dwordx4 v[136:139], v[6:7], off offset:128
	v_add_co_u32_e32 v2, vcc, s14, v0
	s_mov_b32 s14, 0x65c0000
	s_nop 0
	v_addc_co_u32_e32 v3, vcc, 0, v1, vcc
	v_add_co_u32_e32 v0, vcc, s14, v0
	s_nop 1
	v_addc_co_u32_e32 v1, vcc, 0, v1, vcc
	global_load_dwordx4 v[140:143], v[2:3], off offset:128
	global_load_dwordx4 v[144:147], v[0:1], off offset:128
	v_mov_b32_e32 v0, v234
	v_cmp_neq_f32_e32 vcc, s42, v4
	s_nop 0
	v_and_b32_e32 v246, 15, v0
	v_bfe_u32 v247, v0, 4, 2
	v_cndmask_b32_e32 v5, 0, v4, vcc
	s_setprio 1
	v_lshlrev_b32_e32 v1, 4, v247
	v_mul_u32_u24_e32 v2, 0x210, v246
	v_add3_u32 v14, 16, v1, v2
	v_xor_b32_e32 v0, 0x80000000, v5
	v_mov_b32_e32 v1, v0
	v_mov_b32_e32 v2, v0
	v_mov_b32_e32 v3, v0
	ds_read_b128 v[6:9], v14
	ds_read_b128 v[10:13], v14 offset:8448
	ds_read_b128 v[160:163], v14 offset:16896
	s_waitcnt lgkmcnt(2)
	s_nop 0
	v_mfma_f32_16x16x32_bf16 v[148:151], v[6:9], v[84:87], v[0:3]
	ds_read_b128 v[6:9], v14 offset:25344
	s_waitcnt lgkmcnt(2)
	v_mfma_f32_16x16x32_bf16 v[152:155], v[10:13], v[84:87], v[0:3]
	ds_read_b128 v[10:13], v14 offset:64
	s_waitcnt lgkmcnt(2)
	v_mfma_f32_16x16x32_bf16 v[156:159], v[160:163], v[84:87], v[0:3]
	ds_read_b128 v[160:163], v14 offset:8512
	s_waitcnt lgkmcnt(2)
	v_mfma_f32_16x16x32_bf16 v[0:3], v[6:9], v[84:87], v[0:3]
	ds_read_b128 v[6:9], v14 offset:16960
	s_waitcnt lgkmcnt(2)
	v_mfma_f32_16x16x32_bf16 v[148:151], v[10:13], v[76:79], v[148:151]
	ds_read_b128 v[10:13], v14 offset:25408
	s_waitcnt lgkmcnt(2)
	v_mfma_f32_16x16x32_bf16 v[152:155], v[160:163], v[76:79], v[152:155]
	ds_read_b128 v[160:163], v14 offset:128
	s_waitcnt lgkmcnt(2)
	v_mfma_f32_16x16x32_bf16 v[156:159], v[6:9], v[76:79], v[156:159]
	ds_read_b128 v[6:9], v14 offset:8576
	s_waitcnt lgkmcnt(2)
	v_mfma_f32_16x16x32_bf16 v[0:3], v[10:13], v[76:79], v[0:3]
	ds_read_b128 v[10:13], v14 offset:17024
	s_waitcnt lgkmcnt(2)
	v_mfma_f32_16x16x32_bf16 v[148:151], v[160:163], v[72:75], v[148:151]
	ds_read_b128 v[160:163], v14 offset:25472
	s_waitcnt lgkmcnt(2)
	v_mfma_f32_16x16x32_bf16 v[152:155], v[6:9], v[72:75], v[152:155]
	ds_read_b128 v[6:9], v14 offset:192
	s_waitcnt lgkmcnt(2)
	v_mfma_f32_16x16x32_bf16 v[156:159], v[10:13], v[72:75], v[156:159]
	ds_read_b128 v[10:13], v14 offset:8640
	s_waitcnt lgkmcnt(2)
	v_mfma_f32_16x16x32_bf16 v[0:3], v[160:163], v[72:75], v[0:3]
	ds_read_b128 v[160:163], v14 offset:17088
	s_waitcnt lgkmcnt(2)
	v_mfma_f32_16x16x32_bf16 v[148:151], v[6:9], v[64:67], v[148:151]
	ds_read_b128 v[6:9], v14 offset:25536
	s_waitcnt lgkmcnt(2)
	v_mfma_f32_16x16x32_bf16 v[152:155], v[10:13], v[64:67], v[152:155]
	ds_read_b128 v[10:13], v14 offset:256
	s_waitcnt lgkmcnt(2)
	v_mfma_f32_16x16x32_bf16 v[156:159], v[160:163], v[64:67], v[156:159]
	ds_read_b128 v[160:163], v14 offset:8704
	s_waitcnt lgkmcnt(2)
	v_mfma_f32_16x16x32_bf16 v[0:3], v[6:9], v[64:67], v[0:3]
	ds_read_b128 v[6:9], v14 offset:17152
	s_waitcnt lgkmcnt(2)
	v_mfma_f32_16x16x32_bf16 v[148:151], v[10:13], v[60:63], v[148:151]
	ds_read_b128 v[10:13], v14 offset:25600
	s_waitcnt lgkmcnt(2)
	v_mfma_f32_16x16x32_bf16 v[152:155], v[160:163], v[60:63], v[152:155]
	ds_read_b128 v[160:163], v14 offset:320
	s_waitcnt lgkmcnt(2)
	v_mfma_f32_16x16x32_bf16 v[156:159], v[6:9], v[60:63], v[156:159]
	ds_read_b128 v[6:9], v14 offset:8768
	s_waitcnt lgkmcnt(2)
	v_mfma_f32_16x16x32_bf16 v[0:3], v[10:13], v[60:63], v[0:3]
	ds_read_b128 v[10:13], v14 offset:17216
	s_waitcnt lgkmcnt(2)
	v_mfma_f32_16x16x32_bf16 v[148:151], v[160:163], v[52:55], v[148:151]
	ds_read_b128 v[160:163], v14 offset:25664
	s_waitcnt lgkmcnt(2)
	v_mfma_f32_16x16x32_bf16 v[152:155], v[6:9], v[52:55], v[152:155]
	ds_read_b128 v[6:9], v14 offset:384
	s_waitcnt lgkmcnt(2)
	v_mfma_f32_16x16x32_bf16 v[156:159], v[10:13], v[52:55], v[156:159]
	ds_read_b128 v[10:13], v14 offset:8832
	s_waitcnt lgkmcnt(2)
;   DI void tile(const u16* Ks, const u16* Vts) {
;     ...
;       for (int ks = 0; ks < DK / 32; ++ks) {
;         bf16x8 kf = *reinterpret_cast<const bf16x8*>(Ks + (kb * 16 + fr) * KSTR + ks * 32 + fq * 8);
; #pragma unroll
;         for (int qb = 0; qb < NQB; ++qb) s[kb][qb] = __builtin_amdgcn_mfma_f32_16x16x32_bf16(kf, qf[qb][ks], s[kb][qb], 0, 0, 0);
;       }
;     }
;     __builtin_amdgcn_s_setprio(0);
;     bf16x8 pf[NQB][2];
; #pragma unroll
;     for (int qb = 0; qb < NQB; ++qb) {
;       float mx = -INFINITY;
; #pragma unroll
;       for (int kb = 0; kb < 4; ++kb) {
; #pragma unroll
;         for (int j = 0; j < 4; ++j) mx = fmaxf(mx, s[kb][qb][j]); }
;       mx = fmaxf(mx, __shfl_xor(mx, 16));
;       mx = fmaxf(mx, __shfl_xor(mx, 32));
;       const float mn = fmaxf(m[qb], base[qb] + mx);
;       const bool changed = __any(mn > m[qb]);
;       float sum = 0.f;
;       if (changed) {
;         const float delta = mn - base[qb];
;         const float alpha = __builtin_amdgcn_exp2f(m[qb] - mn);
; #pragma unroll
;         for (int kb = 0; kb < 4; ++kb) {
; #pragma unroll
;           for (int j = 0; j < 4; ++j) { float e = __builtin_amdgcn_exp2f(s[kb][qb][j] - delta); s[kb][qb][j] = e; sum += e; } }
;         l[qb] = l[qb] * alpha + sum;
; #pragma unroll
;         for (int d = 0; d < DV / 16; ++d) { o[qb][d][0] *= alpha; o[qb][d][1] *= alpha; o[qb][d][2] *= alpha; o[qb][d][3] *= alpha; }
	v_mfma_f32_16x16x32_bf16 v[0:3], v[160:163], v[52:55], v[0:3]
	ds_read_b128 v[160:163], v14 offset:17280
	s_waitcnt lgkmcnt(2)
	v_mfma_f32_16x16x32_bf16 v[148:151], v[6:9], v[44:47], v[148:151]
	ds_read_b128 v[6:9], v14 offset:25728
	s_waitcnt lgkmcnt(2)
	v_mfma_f32_16x16x32_bf16 v[152:155], v[10:13], v[44:47], v[152:155]
	ds_read_b128 v[10:13], v14 offset:448
	s_waitcnt lgkmcnt(2)
	v_mfma_f32_16x16x32_bf16 v[156:159], v[160:163], v[44:47], v[156:159]
	ds_read_b128 v[160:163], v14 offset:8896
	s_waitcnt lgkmcnt(2)
	v_mfma_f32_16x16x32_bf16 v[0:3], v[6:9], v[44:47], v[0:3]
	ds_read_b128 v[6:9], v14 offset:17344
	s_waitcnt lgkmcnt(2)
	v_mfma_f32_16x16x32_bf16 v[148:151], v[10:13], v[36:39], v[148:151]
	ds_read_b128 v[10:13], v14 offset:25792
	s_waitcnt lgkmcnt(2)
	v_mfma_f32_16x16x32_bf16 v[152:155], v[160:163], v[36:39], v[152:155]
	s_waitcnt lgkmcnt(1)
	v_mfma_f32_16x16x32_bf16 v[156:159], v[6:9], v[36:39], v[156:159]
	s_waitcnt lgkmcnt(0)
	v_mfma_f32_16x16x32_bf16 v[160:163], v[10:13], v[36:39], v[0:3]
	s_setprio 0
	s_nop 3
	v_max3_f32 v2, v148, s42, v149
	v_max3_f32 v2, v2, v150, v151
	v_max3_f32 v2, v2, v152, v153
	v_and_b32_e32 v1, 64, v239
	v_max3_f32 v2, v2, v154, v155
	v_xor_b32_e32 v0, 16, v239
	v_add_u32_e32 v1, 64, v1
	v_max3_f32 v2, v2, v156, v157
	v_cmp_lt_i32_e32 vcc, v0, v1
	v_max3_f32 v2, v2, v158, v159
	v_max3_f32 v2, v2, v160, v161
	v_cndmask_b32_e32 v0, v239, v0, vcc
	v_max3_f32 v2, v2, v162, v163
	v_lshlrev_b32_e32 v16, 2, v0
	ds_bpermute_b32 v0, v16, v2
	v_xor_b32_e32 v3, 32, v239
	v_cmp_lt_i32_e32 vcc, v3, v1
	s_waitcnt lgkmcnt(0)
	v_max_f32_e32 v0, v0, v0
	v_cndmask_b32_e32 v1, v239, v3, vcc
	v_lshlrev_b32_e32 v18, 2, v1
	v_max_f32_e32 v0, v2, v0
	ds_bpermute_b32 v1, v18, v0
	s_waitcnt lgkmcnt(0)
	v_max_f32_e32 v1, v1, v1
	v_max_f32_e32 v0, v0, v1
	v_add_f32_e32 v0, v5, v0
	v_max_f32_e32 v1, v4, v4
	v_max_f32_e32 v251, v1, v0
	v_cmp_gt_f32_e32 vcc, v251, v4
	s_cbranch_vccz .LBB0_150
	v_sub_f32_e32 v15, v251, v5
	v_sub_f32_e32 v0, v148, v15
	v_exp_f32_e32 v0, v0
	v_sub_f32_e32 v1, v149, v15
	v_exp_f32_e32 v1, v1
	v_sub_f32_e32 v2, v150, v15
	v_exp_f32_e32 v2, v2
	v_sub_f32_e32 v3, v151, v15
	v_sub_f32_e32 v19, v4, v251
	v_exp_f32_e32 v3, v3
	v_sub_f32_e32 v4, v152, v15
	v_add_f32_e32 v5, 0, v0
	v_exp_f32_e32 v4, v4
	v_add_f32_e32 v5, v1, v5
	v_add_f32_e32 v5, v2, v5
	v_add_f32_e32 v5, v3, v5
	v_add_f32_e32 v9, v4, v5
	v_sub_f32_e32 v5, v153, v15
	v_exp_f32_e32 v5, v5
	v_sub_f32_e32 v6, v154, v15
	v_exp_f32_e32 v6, v6
	v_sub_f32_e32 v7, v155, v15
	v_exp_f32_e32 v7, v7
	v_sub_f32_e32 v8, v156, v15
	v_exp_f32_e32 v8, v8
	v_add_f32_e32 v9, v5, v9
	v_add_f32_e32 v9, v6, v9
	v_add_f32_e32 v9, v7, v9
	v_add_f32_e32 v13, v8, v9
	v_sub_f32_e32 v9, v157, v15
	v_exp_f32_e32 v9, v9
	v_sub_f32_e32 v10, v158, v15
	v_exp_f32_e32 v10, v10
	v_sub_f32_e32 v11, v159, v15
	v_exp_f32_e32 v11, v11
	v_sub_f32_e32 v12, v160, v15
	v_exp_f32_e32 v12, v12
	v_add_f32_e32 v13, v9, v13
	v_add_f32_e32 v13, v10, v13
	v_add_f32_e32 v13, v11, v13
	v_add_f32_e32 v165, v12, v13
	v_sub_f32_e32 v13, v161, v15
	v_exp_f32_e32 v13, v13
	v_sub_f32_e32 v14, v162, v15
	v_exp_f32_e32 v14, v14
	v_sub_f32_e32 v15, v163, v15
	v_exp_f32_e32 v15, v15
	v_exp_f32_e32 v164, v19
	v_add_f32_e32 v19, v13, v165
	v_add_f32_e32 v19, v14, v19
	v_add_f32_e32 v19, v15, v19
	v_fmac_f32_e32 v19, v252, v164
	v_pk_mul_f32 v[226:227], v[22:23], v[164:165] op_sel_hi:[1,0]
	v_pk_mul_f32 v[224:225], v[20:21], v[164:165] op_sel_hi:[1,0]
	v_pk_mul_f32 v[222:223], v[26:27], v[164:165] op_sel_hi:[1,0]
	v_pk_mul_f32 v[220:221], v[24:25], v[164:165] op_sel_hi:[1,0]
	v_pk_mul_f32 v[218:219], v[30:31], v[164:165] op_sel_hi:[1,0]
	v_pk_mul_f32 v[216:217], v[28:29], v[164:165] op_sel_hi:[1,0]
	v_pk_mul_f32 v[214:215], v[34:35], v[164:165] op_sel_hi:[1,0]
	v_pk_mul_f32 v[212:213], v[32:33], v[164:165] op_sel_hi:[1,0]
	v_pk_mul_f32 v[210:211], v[42:43], v[164:165] op_sel_hi:[1,0]
	v_pk_mul_f32 v[208:209], v[40:41], v[164:165] op_sel_hi:[1,0]
	v_pk_mul_f32 v[206:207], v[50:51], v[164:165] op_sel_hi:[1,0]
	v_pk_mul_f32 v[204:205], v[48:49], v[164:165] op_sel_hi:[1,0]
	v_pk_mul_f32 v[202:203], v[58:59], v[164:165] op_sel_hi:[1,0]
	v_pk_mul_f32 v[200:201], v[56:57], v[164:165] op_sel_hi:[1,0]
	v_pk_mul_f32 v[198:199], v[70:71], v[164:165] op_sel_hi:[1,0]
	v_pk_mul_f32 v[196:197], v[68:69], v[164:165] op_sel_hi:[1,0]
	v_pk_mul_f32 v[194:195], v[82:83], v[164:165] op_sel_hi:[1,0]
	v_pk_mul_f32 v[192:193], v[80:81], v[164:165] op_sel_hi:[1,0]
	v_pk_mul_f32 v[190:191], v[90:91], v[164:165] op_sel_hi:[1,0]
	v_pk_mul_f32 v[188:189], v[88:89], v[164:165] op_sel_hi:[1,0]
	v_pk_mul_f32 v[186:187], v[94:95], v[164:165] op_sel_hi:[1,0]
	v_pk_mul_f32 v[184:185], v[92:93], v[164:165] op_sel_hi:[1,0]
	v_pk_mul_f32 v[182:183], v[98:99], v[164:165] op_sel_hi:[1,0]
	v_pk_mul_f32 v[180:181], v[96:97], v[164:165] op_sel_hi:[1,0]
	v_pk_mul_f32 v[178:179], v[102:103], v[164:165] op_sel_hi:[1,0]
	v_pk_mul_f32 v[176:177], v[100:101], v[164:165] op_sel_hi:[1,0]
	v_pk_mul_f32 v[174:175], v[106:107], v[164:165] op_sel_hi:[1,0]
	v_pk_mul_f32 v[172:173], v[104:105], v[164:165] op_sel_hi:[1,0]
	v_pk_mul_f32 v[170:171], v[110:111], v[164:165] op_sel_hi:[1,0]
	v_pk_mul_f32 v[168:169], v[108:109], v[164:165] op_sel_hi:[1,0]
	v_pk_mul_f32 v[166:167], v[114:115], v[164:165] op_sel_hi:[1,0]
	v_pk_mul_f32 v[164:165], v[112:113], v[164:165] op_sel_hi:[1,0]
	s_cbranch_execnz .LBB0_148

; DI int ltid() { int t = threadIdx.x; asm volatile("" : "+v"(t)); return t; }
; #define load_tile(kt) do { \
;     kreg0 = *reinterpret_cast<const uint4*>(kbase0 + (size_t)(kt) * 64 * 1024); \
;     kreg1 = *reinterpret_cast<const uint4*>(kbase1 + (size_t)(kt) * 64 * 1024); \
;     vreg0 = *reinterpret_cast<const uint4*>(vbase0 + (kt) * 64); \
;     vreg1 = *reinterpret_cast<const uint4*>(vbase1 + (kt) * 64); } while (0)
; #define store_tile() do { \
;     *reinterpret_cast<uint4*>(kdst0) = kreg0; *reinterpret_cast<uint4*>(kdst1) = kreg1; \
;     *reinterpret_cast<uint4*>(vdst0) = vreg0; *reinterpret_cast<uint4*>(vdst1) = vreg1; } while (0)
;   DI void tile(const u16* Ks, const u16* Vts) {
;     ...
;     const int lane = ltid() & 63, fr = lane & 15, fq = lane >> 4;
;     float base[NQB];
; #pragma unroll
;     for (int qb = 0; qb < NQB; ++qb) base[qb] = (m[qb] == -INFINITY) ? 0.f : m[qb];
;     f32x4 s[4][NQB];
;     __builtin_amdgcn_s_setprio(1);
; #pragma unroll
;     for (int kb = 0; kb < 4; ++kb) {
; #pragma unroll
;       for (int qb = 0; qb < NQB; ++qb) s[kb][qb] = f32x4{-base[qb], -base[qb], -base[qb], -base[qb]};
; #pragma unroll
;       for (int ks = 0; ks < DK / 32; ++ks) {
;         bf16x8 kf = *reinterpret_cast<const bf16x8*>(Ks + (kb * 16 + fr) * KSTR + ks * 32 + fq * 8);
; #pragma unroll
;         for (int qb = 0; qb < NQB; ++qb) s[kb][qb] = __builtin_amdgcn_mfma_f32_16x16x32_bf16(kf, qf[qb][ks], s[kb][qb], 0, 0, 0);
;       }
;     }
;     __builtin_amdgcn_s_setprio(0);
;     bf16x8 pf[NQB][2];
; #pragma unroll
;     for (int qb = 0; qb < NQB; ++qb) {
;       float mx = -INFINITY;
; #pragma unroll
;       for (int kb = 0; kb < 4; ++kb) {
; #pragma unroll
;         for (int j = 0; j < 4; ++j) mx = fmaxf(mx, s[kb][qb][j]); }
;       mx = fmaxf(mx, __shfl_xor(mx, 16));
;       mx = fmaxf(mx, __shfl_xor(mx, 32));
;       const float mn = fmaxf(m[qb], base[qb] + mx);
; DI void cross_attn_item(const PRef& p, int tokblk, int h) {
;     ...
;   load_tile(0);
;   for (int kt = 0; kt < 4; ++kt) {
;     __syncthreads();
;     store_tile();
;     __syncthreads();
;     if (kt + 1 < 4) load_tile(kt + 1);
;     fw.tile(Ks, Vts);
.LBB0_151:
	v_mov_b32_e32 v0, v234
	v_cmp_neq_f32_e32 vcc, s42, v251
	s_barrier
	s_waitcnt vmcnt(7)
	ds_write_b128 v250, v[120:123]
	s_waitcnt vmcnt(6)
	ds_write_b128 v250, v[116:119] offset:8448
	s_waitcnt vmcnt(5)
	ds_write_b128 v250, v[124:127] offset:16896
	s_waitcnt vmcnt(4)
	ds_write_b128 v250, v[128:131] offset:25344
	s_waitcnt vmcnt(3)
	ds_write_b128 v249, v[132:135] offset:33792
	s_waitcnt vmcnt(2)
	ds_write_b128 v249, v[136:139] offset:43008
	s_waitcnt vmcnt(1)
	ds_write_b128 v249, v[140:143] offset:52224
	s_waitcnt vmcnt(0)
	ds_write_b128 v249, v[144:147] offset:61440
	s_waitcnt lgkmcnt(0)
	s_barrier
	v_cndmask_b32_e32 v4, 0, v251, vcc
	v_and_b32_e32 v164, 15, v0
	v_bfe_u32 v165, v0, 4, 2
	s_setprio 1
	v_lshlrev_b32_e32 v1, 4, v165
	v_mul_u32_u24_e32 v2, 0x210, v164
	v_add3_u32 v5, 16, v1, v2
	v_xor_b32_e32 v0, 0x80000000, v4
	v_mov_b32_e32 v1, v0
	v_mov_b32_e32 v2, v0
	v_mov_b32_e32 v3, v0
	ds_read_b128 v[6:9], v5
	ds_read_b128 v[10:13], v5 offset:8448
	s_waitcnt lgkmcnt(1)
	s_nop 0
	v_mfma_f32_16x16x32_bf16 v[116:119], v[6:9], v[84:87], v[0:3]
	ds_read_b128 v[6:9], v5 offset:16896
	s_waitcnt lgkmcnt(1)
	v_mfma_f32_16x16x32_bf16 v[120:123], v[10:13], v[84:87], v[0:3]
	ds_read_b128 v[10:13], v5 offset:25344
	s_waitcnt lgkmcnt(1)
	v_mfma_f32_16x16x32_bf16 v[124:127], v[6:9], v[84:87], v[0:3]
	ds_read_b128 v[6:9], v5 offset:64
	s_waitcnt lgkmcnt(1)
	v_mfma_f32_16x16x32_bf16 v[0:3], v[10:13], v[84:87], v[0:3]
	ds_read_b128 v[10:13], v5 offset:8512
	s_waitcnt lgkmcnt(1)
	v_mfma_f32_16x16x32_bf16 v[116:119], v[6:9], v[76:79], v[116:119]
	ds_read_b128 v[6:9], v5 offset:16960
	s_waitcnt lgkmcnt(1)
	v_mfma_f32_16x16x32_bf16 v[120:123], v[10:13], v[76:79], v[120:123]
	ds_read_b128 v[10:13], v5 offset:25408
	s_waitcnt lgkmcnt(1)
	v_mfma_f32_16x16x32_bf16 v[124:127], v[6:9], v[76:79], v[124:127]
	ds_read_b128 v[6:9], v5 offset:128
	s_waitcnt lgkmcnt(1)
	v_mfma_f32_16x16x32_bf16 v[0:3], v[10:13], v[76:79], v[0:3]
	ds_read_b128 v[10:13], v5 offset:8576
	s_waitcnt lgkmcnt(1)
	v_mfma_f32_16x16x32_bf16 v[116:119], v[6:9], v[72:75], v[116:119]
	ds_read_b128 v[6:9], v5 offset:17024
	s_waitcnt lgkmcnt(1)
	v_mfma_f32_16x16x32_bf16 v[120:123], v[10:13], v[72:75], v[120:123]
	ds_read_b128 v[10:13], v5 offset:25472
	s_waitcnt lgkmcnt(1)
	v_mfma_f32_16x16x32_bf16 v[124:127], v[6:9], v[72:75], v[124:127]
	ds_read_b128 v[6:9], v5 offset:192
	s_waitcnt lgkmcnt(1)
	v_mfma_f32_16x16x32_bf16 v[0:3], v[10:13], v[72:75], v[0:3]
	ds_read_b128 v[10:13], v5 offset:8640
	s_waitcnt lgkmcnt(1)
	v_mfma_f32_16x16x32_bf16 v[116:119], v[6:9], v[64:67], v[116:119]
	ds_read_b128 v[6:9], v5 offset:17088
	s_waitcnt lgkmcnt(1)
	v_mfma_f32_16x16x32_bf16 v[120:123], v[10:13], v[64:67], v[120:123]
	ds_read_b128 v[10:13], v5 offset:25536
	s_waitcnt lgkmcnt(1)
	v_mfma_f32_16x16x32_bf16 v[124:127], v[6:9], v[64:67], v[124:127]
	ds_read_b128 v[6:9], v5 offset:256
	s_waitcnt lgkmcnt(1)
	v_mfma_f32_16x16x32_bf16 v[0:3], v[10:13], v[64:67], v[0:3]
	ds_read_b128 v[10:13], v5 offset:8704
	s_waitcnt lgkmcnt(1)
	v_mfma_f32_16x16x32_bf16 v[116:119], v[6:9], v[60:63], v[116:119]
	ds_read_b128 v[6:9], v5 offset:17152
	s_waitcnt lgkmcnt(1)
	v_mfma_f32_16x16x32_bf16 v[120:123], v[10:13], v[60:63], v[120:123]
	ds_read_b128 v[10:13], v5 offset:25600
	s_waitcnt lgkmcnt(1)
	v_mfma_f32_16x16x32_bf16 v[124:127], v[6:9], v[60:63], v[124:127]
	ds_read_b128 v[6:9], v5 offset:320
	s_waitcnt lgkmcnt(1)
	v_mfma_f32_16x16x32_bf16 v[0:3], v[10:13], v[60:63], v[0:3]
	ds_read_b128 v[10:13], v5 offset:8768
	s_waitcnt lgkmcnt(1)
	v_mfma_f32_16x16x32_bf16 v[116:119], v[6:9], v[52:55], v[116:119]
	ds_read_b128 v[6:9], v5 offset:17216
	s_waitcnt lgkmcnt(1)
	v_mfma_f32_16x16x32_bf16 v[120:123], v[10:13], v[52:55], v[120:123]
	ds_read_b128 v[10:13], v5 offset:25664
	s_waitcnt lgkmcnt(1)
	v_mfma_f32_16x16x32_bf16 v[124:127], v[6:9], v[52:55], v[124:127]
	ds_read_b128 v[6:9], v5 offset:384
	s_waitcnt lgkmcnt(1)
	v_mfma_f32_16x16x32_bf16 v[0:3], v[10:13], v[52:55], v[0:3]
	ds_read_b128 v[10:13], v5 offset:8832
	s_waitcnt lgkmcnt(1)
	v_mfma_f32_16x16x32_bf16 v[116:119], v[6:9], v[44:47], v[116:119]
	ds_read_b128 v[6:9], v5 offset:17280
	s_waitcnt lgkmcnt(1)
	v_mfma_f32_16x16x32_bf16 v[120:123], v[10:13], v[44:47], v[120:123]
	ds_read_b128 v[10:13], v5 offset:25728
	s_waitcnt lgkmcnt(1)
	v_mfma_f32_16x16x32_bf16 v[124:127], v[6:9], v[44:47], v[124:127]
	ds_read_b128 v[6:9], v5 offset:448
	s_waitcnt lgkmcnt(1)
	v_mfma_f32_16x16x32_bf16 v[0:3], v[10:13], v[44:47], v[0:3]
	ds_read_b128 v[10:13], v5 offset:8896
	s_waitcnt lgkmcnt(1)
	v_mfma_f32_16x16x32_bf16 v[116:119], v[6:9], v[36:39], v[116:119]
	ds_read_b128 v[6:9], v5 offset:17344
	s_waitcnt lgkmcnt(1)
	v_mfma_f32_16x16x32_bf16 v[120:123], v[10:13], v[36:39], v[120:123]
	ds_read_b128 v[10:13], v5 offset:25792
	s_waitcnt lgkmcnt(1)
	v_mfma_f32_16x16x32_bf16 v[124:127], v[6:9], v[36:39], v[124:127]
	s_waitcnt lgkmcnt(0)
	v_mfma_f32_16x16x32_bf16 v[36:39], v[10:13], v[36:39], v[0:3]
	s_setprio 0
	s_nop 3
	v_max3_f32 v0, v116, s42, v117
	v_max3_f32 v0, v0, v118, v119
	v_max3_f32 v0, v0, v120, v121
	v_max3_f32 v0, v0, v122, v123
	v_max3_f32 v0, v0, v124, v125
	v_max3_f32 v0, v0, v126, v127
	v_max3_f32 v0, v0, v36, v37
	v_max3_f32 v0, v0, v38, v39
	ds_bpermute_b32 v1, v16, v0
	s_waitcnt lgkmcnt(0)
	v_max_f32_e32 v1, v1, v1
	v_max_f32_e32 v0, v0, v1
	ds_bpermute_b32 v1, v18, v0
	s_waitcnt lgkmcnt(0)
	v_max_f32_e32 v1, v1, v1
	v_max_f32_e32 v0, v0, v1
	v_add_f32_e32 v0, v4, v0
	v_max_f32_e32 v1, v251, v251
	v_max_f32_e32 v1, v1, v0
	v_cmp_gt_f32_e32 vcc, v1, v251
	s_cbranch_vccz .LBB0_153
;   DI void tile(const u16* Ks, const u16* Vts) {
;     ...
;       if (changed) {
;         const float delta = mn - base[qb];
;         const float alpha = __builtin_amdgcn_exp2f(m[qb] - mn);
; #pragma unroll
;         for (int kb = 0; kb < 4; ++kb) {
; #pragma unroll
;           for (int j = 0; j < 4; ++j) { float e = __builtin_amdgcn_exp2f(s[kb][qb][j] - delta); s[kb][qb][j] = e; sum += e; } }
;         l[qb] = l[qb] * alpha + sum;
; #pragma unroll
;         for (int d = 0; d < DV / 16; ++d) { o[qb][d][0] *= alpha; o[qb][d][1] *= alpha; o[qb][d][2] *= alpha; o[qb][d][3] *= alpha; }
	v_sub_f32_e32 v15, v1, v4
	v_sub_f32_e32 v0, v116, v15
	v_exp_f32_e32 v0, v0
	v_sub_f32_e32 v44, v251, v1
	v_sub_f32_e32 v1, v117, v15
	v_exp_f32_e32 v1, v1
	v_sub_f32_e32 v2, v118, v15
	v_exp_f32_e32 v2, v2
	v_sub_f32_e32 v3, v119, v15
	v_exp_f32_e32 v3, v3
	v_sub_f32_e32 v4, v120, v15
	v_add_f32_e32 v5, 0, v0
	v_exp_f32_e32 v4, v4
	v_add_f32_e32 v5, v1, v5
	v_add_f32_e32 v5, v2, v5
	v_add_f32_e32 v5, v3, v5
	v_add_f32_e32 v9, v4, v5
	v_sub_f32_e32 v5, v121, v15
	v_exp_f32_e32 v5, v5
	v_sub_f32_e32 v6, v122, v15
	v_exp_f32_e32 v6, v6
	v_sub_f32_e32 v7, v123, v15
	v_exp_f32_e32 v7, v7
	v_sub_f32_e32 v8, v124, v15
	v_exp_f32_e32 v8, v8
	v_add_f32_e32 v9, v5, v9
	v_add_f32_e32 v9, v6, v9
	v_add_f32_e32 v9, v7, v9
	v_add_f32_e32 v13, v8, v9
	v_sub_f32_e32 v9, v125, v15
	v_exp_f32_e32 v9, v9
	v_sub_f32_e32 v10, v126, v15
	v_exp_f32_e32 v10, v10
	v_sub_f32_e32 v11, v127, v15
	v_exp_f32_e32 v11, v11
	v_sub_f32_e32 v12, v36, v15
	v_exp_f32_e32 v12, v12
	v_add_f32_e32 v13, v9, v13
	v_add_f32_e32 v13, v10, v13
	v_add_f32_e32 v13, v11, v13
	v_add_f32_e32 v45, v12, v13
	v_sub_f32_e32 v13, v37, v15
	v_exp_f32_e32 v13, v13
	v_sub_f32_e32 v14, v38, v15
	v_exp_f32_e32 v14, v14
	v_sub_f32_e32 v15, v39, v15
	v_exp_f32_e32 v15, v15
	v_exp_f32_e32 v44, v44
	v_add_f32_e32 v45, v13, v45
	v_add_f32_e32 v45, v14, v45
	v_add_f32_e32 v166, v15, v45
	v_fmac_f32_e32 v166, v19, v44
	v_pk_mul_f32 v[162:163], v[22:23], v[44:45] op_sel_hi:[1,0]
	v_pk_mul_f32 v[160:161], v[20:21], v[44:45] op_sel_hi:[1,0]
	v_pk_mul_f32 v[158:159], v[26:27], v[44:45] op_sel_hi:[1,0]
	v_pk_mul_f32 v[156:157], v[24:25], v[44:45] op_sel_hi:[1,0]
	v_pk_mul_f32 v[154:155], v[30:31], v[44:45] op_sel_hi:[1,0]
	v_pk_mul_f32 v[152:153], v[28:29], v[44:45] op_sel_hi:[1,0]
	v_pk_mul_f32 v[150:151], v[34:35], v[44:45] op_sel_hi:[1,0]
	v_pk_mul_f32 v[148:149], v[32:33], v[44:45] op_sel_hi:[1,0]
	v_pk_mul_f32 v[146:147], v[42:43], v[44:45] op_sel_hi:[1,0]
	v_pk_mul_f32 v[144:145], v[40:41], v[44:45] op_sel_hi:[1,0]
	v_pk_mul_f32 v[142:143], v[50:51], v[44:45] op_sel_hi:[1,0]
	v_pk_mul_f32 v[140:141], v[48:49], v[44:45] op_sel_hi:[1,0]
	v_pk_mul_f32 v[138:139], v[58:59], v[44:45] op_sel_hi:[1,0]
	v_pk_mul_f32 v[136:137], v[56:57], v[44:45] op_sel_hi:[1,0]
	v_pk_mul_f32 v[134:135], v[70:71], v[44:45] op_sel_hi:[1,0]
	v_pk_mul_f32 v[132:133], v[68:69], v[44:45] op_sel_hi:[1,0]
	v_pk_mul_f32 v[130:131], v[82:83], v[44:45] op_sel_hi:[1,0]
	v_pk_mul_f32 v[128:129], v[80:81], v[44:45] op_sel_hi:[1,0]
	v_pk_mul_f32 v[86:87], v[90:91], v[44:45] op_sel_hi:[1,0]
	v_pk_mul_f32 v[84:85], v[88:89], v[44:45] op_sel_hi:[1,0]
	v_pk_mul_f32 v[78:79], v[94:95], v[44:45] op_sel_hi:[1,0]
	v_pk_mul_f32 v[76:77], v[92:93], v[44:45] op_sel_hi:[1,0]
	v_pk_mul_f32 v[74:75], v[98:99], v[44:45] op_sel_hi:[1,0]
	v_pk_mul_f32 v[72:73], v[96:97], v[44:45] op_sel_hi:[1,0]
	v_pk_mul_f32 v[66:67], v[102:103], v[44:45] op_sel_hi:[1,0]
	v_pk_mul_f32 v[64:65], v[100:101], v[44:45] op_sel_hi:[1,0]
	v_pk_mul_f32 v[62:63], v[106:107], v[44:45] op_sel_hi:[1,0]
	v_pk_mul_f32 v[60:61], v[104:105], v[44:45] op_sel_hi:[1,0]
	v_pk_mul_f32 v[54:55], v[110:111], v[44:45] op_sel_hi:[1,0]
	v_pk_mul_f32 v[52:53], v[108:109], v[44:45] op_sel_hi:[1,0]
	v_pk_mul_f32 v[46:47], v[114:115], v[44:45] op_sel_hi:[1,0]
	v_pk_mul_f32 v[44:45], v[112:113], v[44:45] op_sel_hi:[1,0]
	s_cbranch_execnz .LBB0_143
	s_branch .LBB0_154
